# scan1: waves 4-7 delayed by s_sleep 7 before their first chunk (stagger the two waves of each SIMD)
# speedup vs baseline: 1.0070x; 1.0046x over previous
; #define LAS __attribute__((address_space(3)))
; template <int NV, bool WITH_Y, int CH>
; __device__ __forceinline__ void scan_run(f32x2 (&S)[4][8], const unsigned char* oh  , LAS float* wl, float* yout  , int lane) {
;     const int Lc = lane < 56 ? lane : 55, cch = Lc - 16;
;     const bool isw = lane < 16, act = lane < 56;
;     const unsigned char* g0 = oh + Lc * 16;
;     LAS float* l0 = wl + (isw ? 64 + lane * 4 : ((cch >> 3) == 0 ? 0 : 64 + (cch >> 3) * 64) + (cch & 7) * 8);
;     const int cs16 = (lane & 3) * 16, rg4 = (lane >> 2) * 4;
;     u32x4 pa[CH];
; #pragma unroll
;     for (int st = 0; st < CH; ++st) pa[st] = *(const u32x4*)(g0 + (size_t)st * OPTB);
; __device__ __forceinline__ void phase_scan1(const Params& p, const Lt& lt, unsigned char* lds) {
;     ...
;     for (int j = w; j < nslot; j += 8) {
;         int lane = tid & 63; asm volatile("" : "+v"(lane));
;         const int kind = (j ^ (j >> 3)) & 1;
;         const int rank = j >> 1;
;         const int pair = rank * G + lt.bid;
;         if (pair >= NH * NSEG) continue;
;         const int h = pair / NSEG, g = pair % NSEG, row0 = (lane >> 2) * 4, col0 = (lane & 3) * 16;
;         f32x2 S[4][8];
;         const unsigned char* oh = opnd + (size_t)g * SEGLEN * OPTB + h * OPB;
;         float* dst = (kind == 0 ? TG : LG) + (size_t)(h * NSEG + g) * 4096 + row0 * 64 + col0;
;         if (kind == 0) {
; #pragma unroll
;             for (int r = 0; r < 4; ++r)
; #pragma unroll
;                 for (int q = 0; q < 8; ++q) S[r][q] = (f32x2){(row0 + r == col0 + 2 * q) ? 1.f : 0.f, (row0 + r == col0 + 2 * q + 1) ? 1.f : 0.f};
;             scan_run<3, true, 4>(S, oh, wl, (float*)(p.ws + WS_Z) + (size_t)g * SEGLEN * RW + h * 64, lane);
;         } else {
; #pragma unroll
;             for (int r = 0; r < 4; ++r)
; #pragma unroll
;                 for (int q = 0; q < 8; ++q) S[r][q] = (f32x2){0.f, 0.f};
;             scan_run<5, true, 4>(S, oh, wl, (float*)(p.ws + WS_YRAW) + (size_t)g * SEGLEN * RW + h * 64, lane);
.LBB0_265:
	s_ashr_i32 s0, s38, 1
	s_mul_i32 s0, s0, s89
	s_add_i32 s0, s0, s86
	s_cmpk_gt_i32 s0, 0x5ff
	s_cbranch_scc1 .LBB0_264
	s_ashr_i32 s4, s0, 31
	s_lshr_b32 s4, s4, 25
	s_add_i32 s4, s0, s4
	s_lshr_b32 s1, s38, 3
	s_ashr_i32 s47, s4, 7
	s_and_b32 s4, s4, 0xffffff80
	s_xor_b32 s1, s1, s38
	s_sub_i32 s48, s0, s4
	s_and_b32 s1, s1, 1
	s_mul_i32 s4, s48, 0xa8000
	s_mul_hi_i32 s0, s48, 0xa8000
	s_add_u32 s4, s40, s4
	s_mul_i32 s5, s47, 0x380
	s_addc_u32 s0, s41, s0
	s_ashr_i32 s6, s5, 31
	s_add_u32 s30, s4, s5
	s_addc_u32 s31, s0, s6
	s_mul_hi_i32 s49, s48, 0x30000
	s_mul_i32 s50, s48, 0x30000
	s_cmp_eq_u32 s1, 0
	s_cselect_b64 s[28:29], -1, 0
	s_cselect_b32 s34, s45, s42
	s_cselect_b32 s35, s46, s43
	s_cselect_b32 s36, 0, 1.0
	s_cselect_b32 s37, 1.0, 0
	s_lshl_b32 s0, s47, 8
	s_add_u32 s34, s34, s0
	s_addc_u32 s35, s35, 0
	s_add_u32 s34, s34, s50
	s_addc_u32 s35, s35, s49
	v_mov_b32_e32 v0, v106
	v_mov_b32_e32 v1, 0
	v_lshl_add_u64 v[10:11], v[0:1], 2, s[34:35]
	v_min_i32_e32 v2, 55, v106
	v_lshlrev_b32_e32 v0, 4, v2
	v_lshl_add_u64 v[4:5], s[30:31], 0, v[0:1]
	v_add_u32_e32 v0, -16, v2
	v_lshlrev_b32_e32 v1, 3, v0
	v_and_b32_e32 v1, 0xffffffc0, v1
	v_add_u32_e32 v1, 64, v1
	v_cmp_lt_u32_e32 vcc, 7, v0
	s_nop 1
	v_cndmask_b32_e32 v1, 0, v1, vcc
	v_lshlrev_b32_e32 v0, 3, v2
	v_and_or_b32 v1, v0, 56, v1
	v_lshl_add_u32 v0, v106, 2, 64
	v_cmp_gt_u32_e32 vcc, 16, v106
	s_nop 1
	v_cndmask_b32_e32 v1, v1, v0, vcc
	v_lshl_add_u32 v6, v1, 2, s39
	v_cmp_gt_u32_e64 s[0:1], 16, v106
	v_cmp_lt_u32_e64 s[8:9], 15, v106
	v_and_b32_e32 v206, 31, v106
	v_lshrrev_b32_e32 v207, 5, v106
	v_lshl_add_u32 v7, v207, 4, s39
	v_lshlrev_b32_e32 v0, 8, v207
	v_lshl_add_u32 v0, v206, 2, v0
	v_add_u32_e32 v8, s39, v0
	v_lshl_add_u32 v9, v106, 2, s39
	v_lshlrev_b32_e32 v0, 2, v207
	v_sub_u32_e32 v204, v206, v0
	v_mov_b32_e32 v199, s37
	s_mov_b32 s51, 0
	s_mov_b32 s10, 0
	v_lshl_add_u64 v[32:33], v[4:5], 0, s[10:11]
	v_add_co_u32_e32 v34, vcc, s71, v32
	s_nop 1
	v_addc_co_u32_e32 v35, vcc, 0, v33, vcc
	global_load_dwordx4 v[12:15], v[32:33], off
	global_load_dwordx4 v[16:19], v[34:35], off offset:2560
	v_add_co_u32_e32 v34, vcc, 0x5000, v32
	s_nop 1
	v_addc_co_u32_e32 v35, vcc, 0, v33, vcc
	global_load_dwordx4 v[20:23], v[34:35], off offset:1024
	v_add_co_u32_e32 v34, vcc, 0x7000, v32
	s_nop 1
	v_addc_co_u32_e32 v35, vcc, 0, v33, vcc
	global_load_dwordx4 v[24:27], v[34:35], off offset:3584
	v_cmp_eq_u32_e32 vcc, 0, v204
	s_nop 1
	v_cndmask_b32_e32 v128, 0, v199, vcc
	v_cmp_eq_u32_e32 vcc, 1, v204
	s_nop 1
	v_cndmask_b32_e32 v129, 0, v199, vcc
	v_cmp_eq_u32_e32 vcc, 2, v204
	s_nop 1
	v_cndmask_b32_e32 v130, 0, v199, vcc
	v_cmp_eq_u32_e32 vcc, 3, v204
	s_nop 1
	v_cndmask_b32_e32 v131, 0, v199, vcc
	v_cmp_eq_u32_e32 vcc, 8, v204
	s_nop 1
	v_cndmask_b32_e32 v132, 0, v199, vcc
	v_cmp_eq_u32_e32 vcc, 9, v204
	s_nop 1
	v_cndmask_b32_e32 v133, 0, v199, vcc
	v_cmp_eq_u32_e32 vcc, 10, v204
	s_nop 1
	v_cndmask_b32_e32 v134, 0, v199, vcc
	v_cmp_eq_u32_e32 vcc, 11, v204
	s_nop 1
	v_cndmask_b32_e32 v135, 0, v199, vcc
	v_cmp_eq_u32_e32 vcc, 16, v204
	s_nop 1
	v_cndmask_b32_e32 v136, 0, v199, vcc
	v_cmp_eq_u32_e32 vcc, 17, v204
	s_nop 1
	v_cndmask_b32_e32 v137, 0, v199, vcc
	v_cmp_eq_u32_e32 vcc, 18, v204
	s_nop 1
	v_cndmask_b32_e32 v138, 0, v199, vcc
	v_cmp_eq_u32_e32 vcc, 19, v204
	s_nop 1
	v_cndmask_b32_e32 v139, 0, v199, vcc
	v_cmp_eq_u32_e32 vcc, 24, v204
	s_nop 1
	v_cndmask_b32_e32 v140, 0, v199, vcc
	v_cmp_eq_u32_e32 vcc, 25, v204
	s_nop 1
	v_cndmask_b32_e32 v141, 0, v199, vcc
	v_cmp_eq_u32_e32 vcc, 26, v204
	s_nop 1
	v_cndmask_b32_e32 v142, 0, v199, vcc
	v_cmp_eq_u32_e32 vcc, 27, v204
	s_nop 1
	v_cndmask_b32_e32 v143, 0, v199, vcc
	v_mov_b32_e32 v144, 0
	v_mov_b32_e32 v145, 0
	v_mov_b32_e32 v146, 0
	v_mov_b32_e32 v147, 0
	v_mov_b32_e32 v148, 0
	v_mov_b32_e32 v149, 0
	v_mov_b32_e32 v150, 0
	v_mov_b32_e32 v151, 0
	v_mov_b32_e32 v152, 0
	v_mov_b32_e32 v153, 0
	v_mov_b32_e32 v154, 0
	v_mov_b32_e32 v155, 0
	v_mov_b32_e32 v156, 0
	v_mov_b32_e32 v157, 0
	v_mov_b32_e32 v158, 0
	v_mov_b32_e32 v159, 0
	v_mov_b32_e32 v160, 0
	v_mov_b32_e32 v161, 0
	v_mov_b32_e32 v162, 0
	v_mov_b32_e32 v163, 0
	v_mov_b32_e32 v164, 0
	v_mov_b32_e32 v165, 0
	v_mov_b32_e32 v166, 0
	v_mov_b32_e32 v167, 0
	v_mov_b32_e32 v168, 0
	v_mov_b32_e32 v169, 0
	v_mov_b32_e32 v170, 0
	v_mov_b32_e32 v171, 0
	v_mov_b32_e32 v172, 0
	v_mov_b32_e32 v173, 0
	v_mov_b32_e32 v174, 0
	v_mov_b32_e32 v175, 0
	v_cmp_eq_u32_e32 vcc, 0, v204
	s_nop 1
	v_cndmask_b32_e32 v176, 0, v199, vcc
	v_cmp_eq_u32_e32 vcc, 1, v204
	s_nop 1
	v_cndmask_b32_e32 v177, 0, v199, vcc
	v_cmp_eq_u32_e32 vcc, 2, v204
	s_nop 1
	v_cndmask_b32_e32 v178, 0, v199, vcc
	v_cmp_eq_u32_e32 vcc, 3, v204
	s_nop 1
	v_cndmask_b32_e32 v179, 0, v199, vcc
	v_cmp_eq_u32_e32 vcc, 8, v204
	s_nop 1
	v_cndmask_b32_e32 v180, 0, v199, vcc
	v_cmp_eq_u32_e32 vcc, 9, v204
	s_nop 1
	v_cndmask_b32_e32 v181, 0, v199, vcc
	v_cmp_eq_u32_e32 vcc, 10, v204
	s_nop 1
	v_cndmask_b32_e32 v182, 0, v199, vcc
	v_cmp_eq_u32_e32 vcc, 11, v204
	s_nop 1
	v_cndmask_b32_e32 v183, 0, v199, vcc
	v_cmp_eq_u32_e32 vcc, 16, v204
	s_nop 1
	v_cndmask_b32_e32 v184, 0, v199, vcc
	v_cmp_eq_u32_e32 vcc, 17, v204
	s_nop 1
	v_cndmask_b32_e32 v185, 0, v199, vcc
	v_cmp_eq_u32_e32 vcc, 18, v204
	s_nop 1
	v_cndmask_b32_e32 v186, 0, v199, vcc
	v_cmp_eq_u32_e32 vcc, 19, v204
	s_nop 1
	v_cndmask_b32_e32 v187, 0, v199, vcc
	v_cmp_eq_u32_e32 vcc, 24, v204
	s_nop 1
	v_cndmask_b32_e32 v188, 0, v199, vcc
	v_cmp_eq_u32_e32 vcc, 25, v204
	s_nop 1
	v_cndmask_b32_e32 v189, 0, v199, vcc
	v_cmp_eq_u32_e32 vcc, 26, v204
	s_nop 1
	v_cndmask_b32_e32 v190, 0, v199, vcc
	v_cmp_eq_u32_e32 vcc, 27, v204
	s_nop 1
	v_cndmask_b32_e32 v191, 0, v199, vcc
	s_waitcnt vmcnt(0)
	s_and_b32 s4, s38, 12
	s_cmp_lg_u32 s4, 4
	s_cbranch_scc1 .Lscan_nostagger
	s_sleep 7
; #define LAS __attribute__((address_space(3)))
; __device__ __forceinline__ float bflo(unsigned u) { return __uint_as_float(u << 16); }
; __device__ __forceinline__ float bfhi(unsigned u) { return __uint_as_float(u & 0xffff0000u); }
; template <int NV, bool WITH_Y, int CH>
; __device__ __forceinline__ void scan_run(f32x2 (&S)[4][8], const unsigned char* oh  , LAS float* wl, float* yout  , int lane) {
;     ...
;         for (int st = 0; st < CH; ++st) {
;             const u32x4 u = pa[st];
;             const f32x4 lo = isw ? __builtin_bit_cast(f32x4, u) : (f32x4){bflo(u.x), bfhi(u.x), bflo(u.y), bfhi(u.y)};
;             if (act) *(LAS f32x4*)(l0 + st * 384) = lo;
;             if (act && !isw) *(LAS f32x4*)(l0 + st * 384 + 4) = (f32x4){bflo(u.z), bfhi(u.z), bflo(u.w), bfhi(u.w)};
;         }
;         asm volatile("s_waitcnt lgkmcnt(0)" ::: "memory");
;         if (c + 1 < SEGLEN / CH) {
;             const unsigned char* n0 = g0 + (size_t)(c + 1) * CH * OPTB;
; #pragma unroll
;             for (int st = 0; st < CH; ++st) pa[st] = *(const u32x4*)(n0 + (size_t)st * OPTB);
;         }
.Lscan_nostagger:
.Lscan_chunk:
	v_lshlrev_b32_e32 v28, 16, v12
	v_and_b32_e32 v29, 0xffff0000, v12
	v_lshlrev_b32_e32 v30, 16, v13
	v_and_b32_e32 v31, 0xffff0000, v13
	v_cndmask_b32_e64 v31, v31, v15, s[0:1]
	v_cndmask_b32_e64 v30, v30, v14, s[0:1]
	v_cndmask_b32_e64 v29, v29, v13, s[0:1]
	v_cndmask_b32_e64 v28, v28, v12, s[0:1]
	ds_write_b128 v6, v[28:31] offset:0
	v_lshlrev_b32_e32 v28, 16, v16
	v_and_b32_e32 v29, 0xffff0000, v16
	v_lshlrev_b32_e32 v30, 16, v17
	v_and_b32_e32 v31, 0xffff0000, v17
	v_cndmask_b32_e64 v31, v31, v19, s[0:1]
	v_cndmask_b32_e64 v30, v30, v18, s[0:1]
	v_cndmask_b32_e64 v29, v29, v17, s[0:1]
	v_cndmask_b32_e64 v28, v28, v16, s[0:1]
	ds_write_b128 v6, v[28:31] offset:1536
	v_lshlrev_b32_e32 v28, 16, v20
	v_and_b32_e32 v29, 0xffff0000, v20
	v_lshlrev_b32_e32 v30, 16, v21
	v_and_b32_e32 v31, 0xffff0000, v21
	v_cndmask_b32_e64 v31, v31, v23, s[0:1]
	v_cndmask_b32_e64 v30, v30, v22, s[0:1]
	v_cndmask_b32_e64 v29, v29, v21, s[0:1]
	v_cndmask_b32_e64 v28, v28, v20, s[0:1]
	ds_write_b128 v6, v[28:31] offset:3072
	v_lshlrev_b32_e32 v28, 16, v24
	v_and_b32_e32 v29, 0xffff0000, v24
	v_lshlrev_b32_e32 v30, 16, v25
	v_and_b32_e32 v31, 0xffff0000, v25
	v_cndmask_b32_e64 v31, v31, v27, s[0:1]
	v_cndmask_b32_e64 v30, v30, v26, s[0:1]
	v_cndmask_b32_e64 v29, v29, v25, s[0:1]
	v_cndmask_b32_e64 v28, v28, v24, s[0:1]
	ds_write_b128 v6, v[28:31] offset:4608
	s_mov_b64 exec, s[8:9]
	v_lshlrev_b32_e32 v28, 16, v14
	v_and_b32_e32 v29, 0xffff0000, v14
	v_lshlrev_b32_e32 v30, 16, v15
	v_and_b32_e32 v31, 0xffff0000, v15
	ds_write_b128 v6, v[28:31] offset:16
	v_lshlrev_b32_e32 v28, 16, v18
	v_and_b32_e32 v29, 0xffff0000, v18
	v_lshlrev_b32_e32 v30, 16, v19
	v_and_b32_e32 v31, 0xffff0000, v19
	ds_write_b128 v6, v[28:31] offset:1552
	v_lshlrev_b32_e32 v28, 16, v22
	v_and_b32_e32 v29, 0xffff0000, v22
	v_lshlrev_b32_e32 v30, 16, v23
	v_and_b32_e32 v31, 0xffff0000, v23
	ds_write_b128 v6, v[28:31] offset:3088
	v_lshlrev_b32_e32 v28, 16, v26
	v_and_b32_e32 v29, 0xffff0000, v26
	v_lshlrev_b32_e32 v30, 16, v27
	v_and_b32_e32 v31, 0xffff0000, v27
	ds_write_b128 v6, v[28:31] offset:4624
	s_mov_b64 exec, -1
	s_waitcnt lgkmcnt(0)
	s_cmp_eq_u32 s51, 15
	s_cbranch_scc1 .Lscan_noload
	s_add_i32 s10, s51, 1
	s_mul_i32 s10, s10, 0xa800
	v_lshl_add_u64 v[32:33], v[4:5], 0, s[10:11]
	v_add_co_u32_e32 v34, vcc, s71, v32
	s_nop 1
	v_addc_co_u32_e32 v35, vcc, 0, v33, vcc
	global_load_dwordx4 v[12:15], v[32:33], off
	global_load_dwordx4 v[16:19], v[34:35], off offset:2560
	v_add_co_u32_e32 v34, vcc, 0x5000, v32
	s_nop 1
	v_addc_co_u32_e32 v35, vcc, 0, v33, vcc
	global_load_dwordx4 v[20:23], v[34:35], off offset:1024
	v_add_co_u32_e32 v34, vcc, 0x7000, v32
	s_nop 1
	v_addc_co_u32_e32 v35, vcc, 0, v33, vcc
	global_load_dwordx4 v[24:27], v[34:35], off offset:3584
